# P7 v^T stage: second batch of v^T fragment loads issued together with the first
# speedup vs baseline: 1.0017x; 1.0017x over previous
; DI uint2 pk4(f32x4 v) { return make_uint2(pk2(v[0], v[1]), pk2(v[2], v[3])); }
; DI f32x4 mfma16(bf16x8 a, bf16x8 b, f32x4 c) { return __builtin_amdgcn_mfma_f32_16x16x32_bf16(a, b, c, 0, 0, 0); }
; DI void mlstm_out_unit(const Params& p, unsigned char* smem, const int tid, int u) {
;     ...
;         for (int pr = 0; pr < 2; ++pr) {
;             uint2 lo = pk4(X[2 * pr]), hi = pk4(X[2 * pr + 1]);
;             xs[(w * 2 + pr) * 64 + lane] = make_uint4(lo.x, lo.y, hi.x, hi.y);
;         }
;     }
;     __syncthreads();
;     f32x4 acc[4][4];
; #pragma unroll
;     for (int i = 0; i < 4; ++i)
; #pragma unroll
;         for (int j = 0; j < 4; ++j) acc[i][j] = f32x4{0.f, 0.f, 0.f, 0.f};
;     {
;         const bf16_t* qb = q + (tok0 + (lane & 15)) * 128 + (lane >> 4) * 8;
; #pragma unroll
;         for (int ks = 0; ks < 4; ++ks) {
;             bf16x8 bfr[4];
; #pragma unroll
;             for (int i = 0; i < 4; ++i) bfr[i] = ld16(qb + (size_t)i * 16 * 128 + ks * 32);
; #pragma unroll
;             for (int i = 0; i < 4; ++i)
; #pragma unroll
;                 for (int j = 0; j < 4; ++j) acc[i][j] = mfma16(ctf[ks][i], bfr[j], acc[i][j]);
;         }
.LBB0_763:
	s_or_b64 exec, exec, s[86:87]
	v_lshl_add_u64 v[180:181], v[112:113], 0, v[130:131]
	v_add_co_u32_e32 v84, vcc, s3, v180
	s_movk_i32 s86, 0x3000
	s_nop 0
	v_addc_co_u32_e32 v85, vcc, 0, v181, vcc
	v_add_co_u32_e32 v86, vcc, s91, v180
	v_cvt_pk_bf16_f32 v80, v81, v80
	s_nop 0
	v_addc_co_u32_e32 v87, vcc, 0, v181, vcc
	v_add_co_u32_e32 v88, vcc, s86, v180
	v_cvt_pk_bf16_f32 v81, v77, v76
	v_cvt_pk_bf16_f32 v82, v79, v78
	v_cvt_pk_bf16_f32 v83, v73, v72
	v_cvt_pk_bf16_f32 v66, v75, v74
	s_waitcnt lgkmcnt(0)
	v_cvt_pk_bf16_f32 v67, v69, v68
	v_cvt_pk_bf16_f32 v68, v71, v70
	v_cvt_pk_bf16_f32 v69, v65, v64
	v_addc_co_u32_e32 v89, vcc, 0, v181, vcc
	ds_write_b128 v121, v[80:83] offset:4096
	ds_write_b128 v121, v[66:69] offset:5120
	s_waitcnt lgkmcnt(0)
	s_barrier
	s_waitcnt vmcnt(0)
	v_mov_b64_e32 v[64:65], v[188:189]
	v_mov_b64_e32 v[66:67], v[190:191]
	v_mov_b64_e32 v[68:69], v[192:193]
	v_mov_b64_e32 v[70:71], v[194:195]
	v_mov_b64_e32 v[72:73], v[196:197]
	v_mov_b64_e32 v[74:75], v[198:199]
	v_mov_b64_e32 v[76:77], v[200:201]
	v_mov_b64_e32 v[78:79], v[202:203]
	s_waitcnt vmcnt(3)
	v_mfma_f32_16x16x32_bf16 v[80:83], v[52:55], v[64:67], 0
	s_waitcnt vmcnt(2)
	v_mfma_f32_16x16x32_bf16 v[92:95], v[52:55], v[68:71], 0
	s_waitcnt vmcnt(1)
	v_mfma_f32_16x16x32_bf16 v[130:133], v[52:55], v[72:75], 0
	s_waitcnt vmcnt(0)
	v_mfma_f32_16x16x32_bf16 v[52:55], v[52:55], v[76:79], 0
	v_mfma_f32_16x16x32_bf16 v[140:143], v[60:63], v[64:67], 0
	v_mfma_f32_16x16x32_bf16 v[144:147], v[60:63], v[68:71], 0
	v_mfma_f32_16x16x32_bf16 v[148:151], v[60:63], v[72:75], 0
	v_mfma_f32_16x16x32_bf16 v[60:63], v[60:63], v[76:79], 0
	v_mfma_f32_16x16x32_bf16 v[152:155], v[56:59], v[64:67], 0
	v_mfma_f32_16x16x32_bf16 v[156:159], v[56:59], v[68:71], 0
	v_mfma_f32_16x16x32_bf16 v[160:163], v[56:59], v[72:75], 0
	v_mfma_f32_16x16x32_bf16 v[56:59], v[56:59], v[76:79], 0
	v_mfma_f32_16x16x32_bf16 v[64:67], v[48:51], v[64:67], 0
	v_mfma_f32_16x16x32_bf16 v[68:71], v[48:51], v[68:71], 0
	v_mfma_f32_16x16x32_bf16 v[72:75], v[48:51], v[72:75], 0
	v_mfma_f32_16x16x32_bf16 v[48:51], v[48:51], v[76:79], 0
	v_mov_b64_e32 v[76:77], v[204:205]
	v_mov_b64_e32 v[78:79], v[206:207]
	v_mov_b64_e32 v[164:165], v[208:209]
	v_mov_b64_e32 v[166:167], v[210:211]
	v_mov_b64_e32 v[168:169], v[212:213]
	v_mov_b64_e32 v[170:171], v[214:215]
	v_mov_b64_e32 v[172:173], v[216:217]
	v_mov_b64_e32 v[174:175], v[218:219]
	s_waitcnt vmcnt(3)
	v_mfma_f32_16x16x32_bf16 v[80:83], v[44:47], v[76:79], v[80:83]
	s_waitcnt vmcnt(2)
	v_mfma_f32_16x16x32_bf16 v[92:95], v[44:47], v[164:167], v[92:95]
	s_waitcnt vmcnt(1)
	v_mfma_f32_16x16x32_bf16 v[130:133], v[44:47], v[168:171], v[130:133]
	s_waitcnt vmcnt(0)
	v_mfma_f32_16x16x32_bf16 v[44:47], v[44:47], v[172:175], v[52:55]
	v_mfma_f32_16x16x32_bf16 v[52:55], v[40:43], v[76:79], v[140:143]
	v_mfma_f32_16x16x32_bf16 v[140:143], v[40:43], v[164:167], v[144:147]
	v_mfma_f32_16x16x32_bf16 v[144:147], v[40:43], v[168:171], v[148:151]
	v_mfma_f32_16x16x32_bf16 v[60:63], v[40:43], v[172:175], v[60:63]
	v_mfma_f32_16x16x32_bf16 v[148:151], v[36:39], v[76:79], v[152:155]
	v_mfma_f32_16x16x32_bf16 v[152:155], v[36:39], v[164:167], v[156:159]
	v_mfma_f32_16x16x32_bf16 v[156:159], v[36:39], v[168:171], v[160:163]
	v_mfma_f32_16x16x32_bf16 v[56:59], v[36:39], v[172:175], v[56:59]
	v_mfma_f32_16x16x32_bf16 v[160:163], v[32:35], v[164:167], v[68:71]
	v_mfma_f32_16x16x32_bf16 v[72:75], v[32:35], v[168:171], v[72:75]
	v_mfma_f32_16x16x32_bf16 v[164:167], v[32:35], v[172:175], v[48:51]
	v_mov_b64_e32 v[168:169], v[220:221]
	v_mov_b64_e32 v[170:171], v[222:223]
	v_mov_b64_e32 v[172:173], v[224:225]
	v_mov_b64_e32 v[174:175], v[226:227]
	v_mov_b64_e32 v[176:177], v[228:229]
	v_mov_b64_e32 v[178:179], v[230:231]
	v_mov_b64_e32 v[184:185], v[232:233]
	v_mov_b64_e32 v[186:187], v[234:235]
	v_mfma_f32_16x16x32_bf16 v[64:67], v[32:35], v[76:79], v[64:67]
	s_waitcnt vmcnt(3)
	v_mfma_f32_16x16x32_bf16 v[80:83], v[24:27], v[168:171], v[80:83]
	s_waitcnt vmcnt(2)
	v_mfma_f32_16x16x32_bf16 v[76:79], v[24:27], v[172:175], v[92:95]
	s_waitcnt vmcnt(1)
	v_mfma_f32_16x16x32_bf16 v[68:71], v[24:27], v[176:179], v[130:133]
	s_waitcnt vmcnt(0)
	v_mfma_f32_16x16x32_bf16 v[24:27], v[24:27], v[184:187], v[44:47]
	v_mfma_f32_16x16x32_bf16 v[32:35], v[28:31], v[168:171], v[52:55]
	v_mfma_f32_16x16x32_bf16 v[44:47], v[20:23], v[168:171], v[148:151]
	v_mfma_f32_16x16x32_bf16 v[48:51], v[20:23], v[172:175], v[152:155]
	v_mfma_f32_16x16x32_bf16 v[52:55], v[20:23], v[176:179], v[156:159]
	v_mfma_f32_16x16x32_bf16 v[20:23], v[20:23], v[184:187], v[56:59]
	v_mfma_f32_16x16x32_bf16 v[56:59], v[16:19], v[168:171], v[64:67]
	v_mfma_f32_16x16x32_bf16 v[64:67], v[16:19], v[176:179], v[72:75]
	s_nop 2
	v_mov_b64_e32 v[72:73], v[236:237]
	v_mov_b64_e32 v[74:75], v[238:239]
	v_mov_b64_e32 v[92:93], v[240:241]
	v_mov_b64_e32 v[94:95], v[242:243]
	s_nop 0
	v_mov_b64_e32 v[84:85], v[244:245]
	v_mov_b64_e32 v[86:87], v[246:247]
	s_nop 0
	v_mov_b64_e32 v[130:131], v[248:249]
	v_mov_b64_e32 v[132:133], v[182:183]
	v_mfma_f32_16x16x32_bf16 v[36:39], v[28:31], v[172:175], v[140:143]
	v_mfma_f32_16x16x32_bf16 v[40:43], v[28:31], v[176:179], v[144:147]
	v_mfma_f32_16x16x32_bf16 v[28:31], v[28:31], v[184:187], v[60:63]
	v_mfma_f32_16x16x32_bf16 v[60:63], v[16:19], v[172:175], v[160:163]
	s_waitcnt vmcnt(3)
	v_mfma_f32_16x16x32_bf16 v[80:83], v[12:15], v[72:75], v[80:83]
	s_waitcnt vmcnt(2)
	v_mfma_f32_16x16x32_bf16 v[76:79], v[12:15], v[92:95], v[76:79]
	s_waitcnt vmcnt(1)
	v_mfma_f32_16x16x32_bf16 v[68:71], v[12:15], v[84:87], v[68:71]
	s_waitcnt vmcnt(0)
; DI f32x4 mfma16(bf16x8 a, bf16x8 b, f32x4 c) { return __builtin_amdgcn_mfma_f32_16x16x32_bf16(a, b, c, 0, 0, 0); }
; DI void mlstm_out_unit(const Params& p, unsigned char* smem, const int tid, int u) {
;     ...
; #pragma unroll
;     for (int ni = 0; ni < 4; ++ni) {
;         const float s = sci[16 * ni + (lane & 15)];
; #pragma unroll
;         for (int mi = 0; mi < 4; ++mi) { acc[mi][ni][0] *= s; acc[mi][ni][1] *= s; acc[mi][ni][2] *= s; acc[mi][ni][3] *= s; }
;     }
;     {
;         const bf16_t* vb = vT + (((size_t)bh * 128 + c) * 256 + 64 * w + ((lane & 15) >> 2) * 8 + (lane & 3)) * 64 + (lane >> 4) * 4;
; #pragma unroll
;         for (int pr = 0; pr < 2; ++pr) {
;             bf16x8 af[4];
; #pragma unroll
;             for (int mi = 0; mi < 4; ++mi) {
;                 uint2 lo = *(const uint2*)(vb + (size_t)((mi >> 1) * 32 + (mi & 1) * 4) * 64 + pr * 32);
;                 uint2 hi = *(const uint2*)(vb + (size_t)((mi >> 1) * 32 + (mi & 1) * 4) * 64 + pr * 32 + 16);
;                 af[mi] = __builtin_bit_cast(bf16x8, make_uint4(lo.x, lo.y, hi.x, hi.y));
;             }
; #pragma unroll
;             for (int ni = 0; ni < 4; ++ni) {
;                 if (ni >= 2 * pr) {
;                     bf16x8 xb = __builtin_bit_cast(bf16x8, xs[(ni * 2 + pr) * 64 + lane]);
; #pragma unroll
;                     for (int mi = 0; mi < 4; ++mi) acc[mi][ni] = mfma16(af[mi], xb, acc[mi][ni]);
	v_mfma_f32_16x16x32_bf16 v[140:143], v[12:15], v[130:133], v[24:27]
	v_mfma_f32_16x16x32_bf16 v[12:15], v[8:11], v[72:75], v[32:35]
	v_mfma_f32_16x16x32_bf16 v[32:35], v[8:11], v[92:95], v[36:39]
	v_mfma_f32_16x16x32_bf16 v[36:39], v[8:11], v[84:87], v[40:43]
	v_mfma_f32_16x16x32_bf16 v[40:43], v[8:11], v[130:133], v[28:31]
	s_nop 2
	ds_read2_b32 v[28:29], v123 offset0:128 offset1:144
	v_mfma_f32_16x16x32_bf16 v[16:19], v[16:19], v[184:187], v[164:167]
	s_waitcnt lgkmcnt(0)
	v_mov_b32_e32 v30, v29
	v_mfma_f32_16x16x32_bf16 v[8:11], v[4:7], v[72:75], v[44:47]
	v_mul_f32_e64 v14, v14, v28
	v_mul_f32_e64 v15, v15, v28
	v_pk_mul_f32 v[12:13], v[12:13], v[28:29] op_sel_hi:[1,0]
	v_mfma_f32_16x16x32_bf16 v[44:47], v[4:7], v[92:95], v[48:51]
	v_mfma_f32_16x16x32_bf16 v[144:147], v[4:7], v[130:133], v[20:23]
	s_nop 2
	v_mul_f32_e64 v10, v10, v28
	v_mul_f32_e64 v11, v11, v28
	v_pk_mul_f32 v[8:9], v[8:9], v[28:29] op_sel_hi:[1,0]
	v_mfma_f32_16x16x32_bf16 v[20:23], v[0:3], v[92:95], v[60:63]
	v_mfma_f32_16x16x32_bf16 v[48:51], v[4:7], v[84:87], v[52:55]
	v_mul_f32_e64 v6, v34, v30
	v_mul_f32_e64 v7, v35, v30
	v_pk_mul_f32 v[4:5], v[32:33], v[30:31] op_sel_hi:[1,0]
	s_nop 3
	v_pk_mul_f32 v[22:23], v[22:23], v[30:31] op_sel_hi:[1,0]
	v_mfma_f32_16x16x32_bf16 v[24:27], v[0:3], v[72:75], v[56:59]
	v_mul_f32_e64 v20, v20, v30
	v_mul_f32_e64 v21, v21, v30
	v_mfma_f32_16x16x32_bf16 v[52:55], v[0:3], v[84:87], v[64:67]
	v_mfma_f32_16x16x32_bf16 v[72:75], v[0:3], v[130:133], v[16:19]
	v_mul_f32_e64 v2, v78, v30
	v_mul_f32_e64 v3, v79, v30
	v_pk_mul_f32 v[0:1], v[76:77], v[30:31] op_sel_hi:[1,0]
	s_nop 0
	v_pk_mul_f32 v[26:27], v[26:27], v[28:29] op_sel_hi:[1,0]
	v_pk_mul_f32 v[18:19], v[46:47], v[30:31] op_sel_hi:[1,0]
	v_pk_mul_f32 v[16:17], v[44:45], v[30:31] op_sel_hi:[1,0]
	ds_read2_b32 v[30:31], v123 offset0:160 offset1:176
	v_pk_mul_f32 v[24:25], v[24:25], v[28:29] op_sel_hi:[1,0]
	s_waitcnt lgkmcnt(0)
	v_pk_mul_f32 v[34:35], v[70:71], v[30:31] op_sel_hi:[1,0]
	v_pk_mul_f32 v[32:33], v[68:69], v[30:31] op_sel_hi:[1,0]
	v_pk_mul_f32 v[38:39], v[38:39], v[30:31] op_sel_hi:[1,0]
	v_pk_mul_f32 v[36:37], v[36:37], v[30:31] op_sel_hi:[1,0]
	v_pk_mul_f32 v[50:51], v[50:51], v[30:31] op_sel_hi:[1,0]
	v_pk_mul_f32 v[48:49], v[48:49], v[30:31] op_sel_hi:[1,0]
	v_pk_mul_f32 v[54:55], v[54:55], v[30:31] op_sel_hi:[1,0]
	v_pk_mul_f32 v[52:53], v[52:53], v[30:31] op_sel_hi:[1,0]
	v_mov_b32_e32 v30, v31
	v_pk_mul_f32 v[58:59], v[142:143], v[30:31] op_sel_hi:[1,0]
	v_pk_mul_f32 v[56:57], v[140:141], v[30:31] op_sel_hi:[1,0]
	v_pk_mul_f32 v[62:63], v[42:43], v[30:31] op_sel_hi:[1,0]
	v_pk_mul_f32 v[60:61], v[40:41], v[30:31] op_sel_hi:[1,0]
	v_pk_mul_f32 v[66:67], v[146:147], v[30:31] op_sel_hi:[1,0]
	v_pk_mul_f32 v[64:65], v[144:145], v[30:31] op_sel_hi:[1,0]
	v_pk_mul_f32 v[70:71], v[74:75], v[30:31] op_sel_hi:[1,0]
	v_pk_mul_f32 v[68:69], v[72:73], v[30:31] op_sel_hi:[1,0]
	v_lshlrev_b64 v[30:31], 7, v[128:129]
	v_lshl_add_u64 v[88:89], v[124:125], 0, v[30:31]
	v_add_co_u32_e32 v130, vcc, s3, v88
	global_load_dwordx2 v[72:73], v[88:89], off
	global_load_dwordx2 v[74:75], v[88:89], off offset:32
	global_load_dwordx2 v[76:77], v[88:89], off offset:512
	global_load_dwordx2 v[78:79], v[88:89], off offset:544
	v_addc_co_u32_e32 v131, vcc, 0, v89, vcc
	global_load_dwordx2 v[84:85], v[130:131], off
	global_load_dwordx2 v[86:87], v[130:131], off offset:32
	global_load_dwordx2 v[92:93], v[130:131], off offset:512
	global_load_dwordx2 v[94:95], v[130:131], off offset:544
	global_load_dwordx2 v[188:189], v[88:89], off offset:64
	global_load_dwordx2 v[190:191], v[88:89], off offset:96
	global_load_dwordx2 v[192:193], v[88:89], off offset:576
	global_load_dwordx2 v[194:195], v[88:89], off offset:608
	global_load_dwordx2 v[196:197], v[130:131], off offset:64
	global_load_dwordx2 v[198:199], v[130:131], off offset:96
	global_load_dwordx2 v[200:201], v[130:131], off offset:576
	global_load_dwordx2 v[202:203], v[130:131], off offset:608
	v_pk_mul_f32 v[30:31], v[82:83], v[28:29] op_sel_hi:[1,0]
	v_pk_mul_f32 v[28:29], v[80:81], v[28:29] op_sel_hi:[1,0]
	ds_read_b128 v[80:83], v119 offset:4096
	s_waitcnt vmcnt(12) lgkmcnt(0)
	v_mfma_f32_16x16x32_bf16 v[40:43], v[76:79], v[80:83], v[12:15]
	v_mfma_f32_16x16x32_bf16 v[44:47], v[72:75], v[80:83], v[28:31]
	s_waitcnt vmcnt(10)
	v_mfma_f32_16x16x32_bf16 v[28:31], v[84:87], v[80:83], v[8:11]
	s_waitcnt vmcnt(8)
; DI void mlstm_out_unit(const Params& p, unsigned char* smem, const int tid, int u) {
;     ...
; #pragma unroll
;             for (int ni = 0; ni < 4; ++ni) {
;                 if (ni >= 2 * pr) {
;                     bf16x8 xb = __builtin_bit_cast(bf16x8, xs[(ni * 2 + pr) * 64 + lane]);
; #pragma unroll
;                     for (int mi = 0; mi < 4; ++mi) acc[mi][ni] = mfma16(af[mi], xb, acc[mi][ni]);
;                 }
;             }
;         }
;     }
; #pragma unroll
;     for (int ni = 0; ni < 4; ++ni) {
;         const float rd = rden[16 * ni + (lane & 15)];
;         float s = 0.f;
; #pragma unroll
;         for (int mi = 0; mi < 4; ++mi) { acc[mi][ni][0] *= rd; acc[mi][ni][1] *= rd; acc[mi][ni][2] *= rd; acc[mi][ni][3] *= rd;
;             s += acc[mi][ni][0] + acc[mi][ni][1] + acc[mi][ni][2] + acc[mi][ni][3]; }
;         s += __shfl_xor(s, 16, 64); s += __shfl_xor(s, 32, 64);
;         if (lane < 16) part[w * 64 + 16 * ni + lane] = s;
;     }
;     __syncthreads();
;     if (tid < 64) mean_s[tid] = (part[tid] + part[64 + tid] + part[128 + tid] + part[192 + tid]) * (1.f / 256.f);
;     __syncthreads();
; #pragma unroll
;     for (int ni = 0; ni < 4; ++ni) {
;         const float mu = mean_s[16 * ni + (lane & 15)];
;         float s = 0.f;
; #pragma unroll
;         for (int mi = 0; mi < 4; ++mi)
; #pragma unroll
;             for (int r = 0; r < 4; ++r) { float d = acc[mi][ni][r] - mu; s += d * d; }
;         s += __shfl_xor(s, 16, 64); s += __shfl_xor(s, 32, 64);
;         if (lane < 16) part[w * 64 + 16 * ni + lane] = s;
;     }
;     __syncthreads();
;     if (tid < 64) rstd_s[tid] = rsqrtf((part[tid] + part[64 + tid] + part[128 + tid] + part[192 + tid]) * (1.f / 256.f) + 1e-5f);
;     __syncthreads();
;     const float* gain = p.in[10];
;     float4 gg[2][2];
;     uint2 ogv[4][2];
;     const int ch_l = h * 256 + 64 * w + (lane >> 4) * 8;
; #pragma unroll
;     for (int k = 0; k < 2; ++k) { gg[k][0] = *(const float4*)(gain + ch_l + 32 * k); gg[k][1] = *(const float4*)(gain + ch_l + 32 * k + 4); }
; #pragma unroll
;     for (int ni = 0; ni < 4; ++ni)
; #pragma unroll
;         for (int k = 0; k < 2; ++k)
;             ogv[ni][k] = *(const uint2*)((const unsigned char*)og + ((size_t)b * 8192 + c * 64 + 16 * ni + (lane & 15)) * 1024 + ch_l + 32 * k);
	v_mfma_f32_16x16x32_bf16 v[24:27], v[92:95], v[80:83], v[24:27]
	ds_read_b128 v[80:83], v119 offset:6144
	s_waitcnt lgkmcnt(0)
	v_mfma_f32_16x16x32_bf16 v[8:11], v[76:79], v[80:83], v[4:7]
	v_mfma_f32_16x16x32_bf16 v[4:7], v[84:87], v[80:83], v[16:19]
	s_nop 2
	ds_read_b128 v[16:19], v119 offset:8192
	v_mfma_f32_16x16x32_bf16 v[12:15], v[72:75], v[80:83], v[0:3]
	v_mfma_f32_16x16x32_bf16 v[0:3], v[92:95], v[80:83], v[20:23]
	s_waitcnt lgkmcnt(0)
	v_mfma_f32_16x16x32_bf16 v[20:23], v[72:75], v[16:19], v[32:35]
	v_mfma_f32_16x16x32_bf16 v[32:35], v[76:79], v[16:19], v[36:39]
	v_mfma_f32_16x16x32_bf16 v[36:39], v[84:87], v[16:19], v[48:51]
	s_nop 2
	ds_read_b128 v[48:51], v119 offset:10240
	v_mfma_f32_16x16x32_bf16 v[16:19], v[92:95], v[16:19], v[52:55]
	s_waitcnt lgkmcnt(0)
	v_mfma_f32_16x16x32_bf16 v[64:67], v[84:87], v[48:51], v[64:67]
	v_mfma_f32_16x16x32_bf16 v[68:71], v[92:95], v[48:51], v[68:71]
	s_waitcnt vmcnt(0)
	v_mov_b64_e32 v[80:81], v[188:189]
	v_mov_b64_e32 v[82:83], v[190:191]
	v_mov_b64_e32 v[84:85], v[192:193]
	v_mov_b64_e32 v[86:87], v[194:195]
	v_mov_b64_e32 v[92:93], v[196:197]
	v_mov_b64_e32 v[94:95], v[198:199]
	v_mov_b64_e32 v[128:129], v[200:201]
	v_mov_b64_e32 v[130:131], v[202:203]
	v_mfma_f32_16x16x32_bf16 v[72:75], v[72:75], v[48:51], v[56:59]
	v_mfma_f32_16x16x32_bf16 v[76:79], v[76:79], v[48:51], v[60:63]
	ds_read_b128 v[48:51], v119 offset:9216
	s_waitcnt vmcnt(6) lgkmcnt(0)
	v_mfma_f32_16x16x32_bf16 v[60:63], v[80:83], v[48:51], v[20:23]
	s_waitcnt vmcnt(4)
	v_mfma_f32_16x16x32_bf16 v[56:59], v[84:87], v[48:51], v[32:35]
	s_waitcnt vmcnt(2)
	v_mfma_f32_16x16x32_bf16 v[52:55], v[92:95], v[48:51], v[36:39]
	s_waitcnt vmcnt(0)
	v_mfma_f32_16x16x32_bf16 v[48:51], v[128:131], v[48:51], v[16:19]
	s_nop 2
	ds_read_b128 v[16:19], v134 offset:4096
	s_waitcnt lgkmcnt(0)
	v_mfma_f32_16x16x32_bf16 v[36:39], v[80:83], v[16:19], v[72:75]
	s_nop 2
	ds_read_b32 v72, v123 offset:1280
	v_mfma_f32_16x16x32_bf16 v[32:35], v[84:87], v[16:19], v[76:79]
	v_mfma_f32_16x16x32_bf16 v[20:23], v[92:95], v[16:19], v[64:67]
	v_mfma_f32_16x16x32_bf16 v[16:19], v[128:131], v[16:19], v[68:71]
	v_readlane_b32 s76, v254, 40
	v_readlane_b32 s77, v254, 41
	v_ashrrev_i32_e32 v220, 9, v97
	v_lshlrev_b32_e32 v222, 8, v126
	s_movk_i32 s74, 0x300
	v_ashrrev_i32_e32 v221, 31, v220
	v_and_or_b32 v222, v222, s74, v136
	v_lshlrev_b64 v[220:221], 13, v[220:221]
	v_mov_b32_e32 v223, 0
	v_or_b32_e32 v220, v220, v139
	v_lshlrev_b32_e32 v226, 2, v222
	v_or_b32_e32 v220, v220, v104
	v_lshl_add_u64 v[224:225], s[72:73], 0, v[222:223]
	v_lshlrev_b64 v[220:221], 10, v[220:221]
	global_load_dwordx4 v[188:191], v226, s[76:77] offset:16
	global_load_dwordx4 v[192:195], v226, s[76:77]
	v_lshl_add_u64 v[224:225], v[224:225], 0, v[220:221]
	global_load_dwordx4 v[196:199], v226, s[76:77] offset:144
	global_load_dwordx4 v[200:203], v226, s[76:77] offset:128
	s_mov_b64 s[78:79], 0x4000
	s_mov_b64 s[80:81], 0x8000
	s_mov_b64 s[82:83], 0xc000
	v_lshl_add_u64 v[228:229], v[224:225], 0, s[78:79]
	global_load_dwordx2 v[204:205], v[224:225], off
	global_load_dwordx2 v[206:207], v[224:225], off offset:32
	v_lshl_add_u64 v[230:231], v[224:225], 0, s[80:81]
	global_load_dwordx2 v[208:209], v[228:229], off
	global_load_dwordx2 v[210:211], v[228:229], off offset:32
	v_lshl_add_u64 v[232:233], v[224:225], 0, s[82:83]
	global_load_dwordx2 v[212:213], v[230:231], off
	global_load_dwordx2 v[214:215], v[230:231], off offset:32
	global_load_dwordx2 v[216:217], v[232:233], off
	global_load_dwordx2 v[218:219], v[232:233], off offset:32
	s_waitcnt lgkmcnt(0)
	s_nop 1
	v_mul_f32_e32 v70, v45, v72
	v_fma_f32 v45, v44, v72, v70
	v_mul_f32_e32 v71, v41, v72
	v_fmac_f32_e32 v45, v46, v72
	v_fma_f32 v41, v40, v72, v71
	v_mul_f32_e32 v69, v29, v72
	v_fmac_f32_e32 v45, v47, v72
	v_fmac_f32_e32 v41, v42, v72
	v_fma_f32 v29, v28, v72, v69
	v_mul_f32_e32 v68, v25, v72
	v_add_f32_e32 v45, 0, v45
	v_fmac_f32_e32 v41, v43, v72
	v_fmac_f32_e32 v29, v30, v72
	v_fma_f32 v25, v24, v72, v68
	v_add_f32_e32 v41, v41, v45
	v_fmac_f32_e32 v29, v31, v72
	v_fmac_f32_e32 v25, v26, v72
	v_add_f32_e32 v29, v29, v41
	v_fmac_f32_e32 v25, v27, v72
	v_add_f32_e32 v25, v25, v29
	ds_bpermute_b32 v29, v90, v25
	s_waitcnt lgkmcnt(0)
	v_add_f32_e32 v25, v25, v29
	ds_bpermute_b32 v29, v91, v25
	s_and_saveexec_b64 s[86:87], s[12:13]
	s_cbranch_execz .LBB0_765
	s_waitcnt lgkmcnt(0)
	v_add_f32_e32 v25, v25, v29
	ds_write_b32 v135, v25 offset:1536
